# baseline (speedup 1.0000x reference)
; #define WAIT_V(n) asm volatile("s_waitcnt vmcnt(%0)" ::"n"(n) : "memory")
;     ...
;     for (int t = 0; t < nt; ++t) {
;       const int cur = t & 1;
;       const char* sa = shm + cur * STAGE_B;
;       const char* sn = shm + (cur ^ 1) * STAGE_B;
;       const bool more = (t + 1 < nt) || (nitem < ntiles);
; #pragma unroll
;       for (int ks = 0; ks < 2; ++ks) {
; #pragma unroll
;         for (int p = 0; p < NP; ++p) {
;           const int q = ks * NP + p;
;           acc[p * 2][0] = __builtin_amdgcn_mfma_f32_16x16x32_bf16(Bq[BDBL ? ks : 0][0], Aq[q & 1][0], acc[p * 2][0], 0, 0, 0);
;           __builtin_amdgcn_sched_barrier(0);
;           if (q == 2 * NP - 1) {
;             WAIT_V(0);
;             __syncthreads();
;             if (more) {
;               if constexpr (BDBL) {
; #pragma unroll
;                 for (int n = 0; n < 4; ++n) Bq[0][n] = *(const bf16x8*)(sn + boff + (n * 2 + 0) * 1024);
;               }
; #pragma unroll
;               for (int i = 0; i < 2; ++i) Aq[0][i] = *(const bf16x8*)(sn + aoff + (i * 2 + 0) * 1024);
;             }
;           } else if (p + 1 < NP) {
; #pragma unroll
;             for (int i = 0; i < 2; ++i) Aq[(q + 1) & 1][i] = *(const bf16x8*)(sa + aoff + (((p + 1) * 2 + i) * 2 + ks) * 1024);
;           } else {
;             if constexpr (BDBL) {
; #pragma unroll
;               for (int n = 0; n < 4; ++n) Bq[1][n] = *(const bf16x8*)(sa + boff + (n * 2 + 1) * 1024);
;             }
; #pragma unroll
;             for (int i = 0; i < 2; ++i) Aq[(q + 1) & 1][i] = *(const bf16x8*)(sa + aoff + (i * 2 + 1) * 1024);
;           }
;           __builtin_amdgcn_sched_barrier(0);
; #pragma unroll
;           for (int i = 0; i < 2; ++i)
; #pragma unroll
;             for (int n = 0; n < 4; ++n)
;               if (i + n > 0)
;                 acc[p * 2 + i][n] = __builtin_amdgcn_mfma_f32_16x16x32_bf16(Bq[BDBL ? ks : 0][n], Aq[q & 1][i], acc[p * 2 + i][n], 0, 0, 0);
;           __builtin_amdgcn_sched_barrier(0);
;           if (q == GLDS_AT) {
;             if (t + 1 < nt) GLDS_STAGE(cur ^ 1, t + 1, Ab, Bb);
;             else if (nitem < ntiles) GLDS_STAGE(0, 0, nAb, nBb);
;             __builtin_amdgcn_sched_barrier(0);
;           }
.LBB0_741:
	v_lshl_add_u64 v[152:153], s[16:17], 0, v[220:221]
	v_lshl_add_u64 v[154:155], s[14:15], 0, v[220:221]
	s_mov_b64 s[0:1], 0
	s_waitcnt lgkmcnt(0)
	s_nop 0
	v_mfma_f32_16x16x32_bf16 v[148:151], v[4:7], v[20:23], 0
	s_and_b32 s14, s22, 0x10000
	s_xor_b32 s15, s14, 0x10000
	v_add_u32_e32 v168, s14, v222
	v_add_u32_e32 v169, s15, v222
	v_bitop3_b32 v170, s22, v223, v233 bitop3:0xce
	v_or_b32_e32 v171, s14, v223
	ds_read_b128 v[156:159], v168 offset:4096
	ds_read_b128 v[160:163], v168 offset:6144
	v_mfma_f32_16x16x32_bf16 v[144:147], v[0:3], v[20:23], 0
	s_add_i32 s14, s15, s4
	v_lshl_add_u64 v[164:165], v[152:153], 0, s[0:1]
	v_mfma_f32_16x16x32_bf16 v[140:143], v[12:15], v[20:23], 0
	v_lshl_add_u64 v[166:167], v[164:165], 0, s[38:39]
	s_mov_b32 m0, s14
	v_mfma_f32_16x16x32_bf16 v[20:23], v[8:11], v[20:23], 0
	s_add_i32 s15, s14, 0x8000
	global_load_lds_dwordx4 v[166:167], off
	v_mfma_f32_16x16x32_bf16 v[132:135], v[4:7], v[16:19], 0
	v_lshl_add_u64 v[166:167], v[164:165], 0, s[82:83]
	s_add_i32 m0, s14, 0x2000
	v_mfma_f32_16x16x32_bf16 v[128:131], v[0:3], v[16:19], 0
	global_load_lds_dwordx4 v[166:167], off
	v_lshl_add_u64 v[166:167], v[164:165], 0, s[78:79]
	v_mfma_f32_16x16x32_bf16 v[124:127], v[12:15], v[16:19], 0
	s_add_i32 m0, s14, 0x4000
	v_lshl_add_u64 v[164:165], v[164:165], 0, s[2:3]
	v_mfma_f32_16x16x32_bf16 v[16:19], v[8:11], v[16:19], 0
	global_load_lds_dwordx4 v[166:167], off
	s_add_i32 m0, s14, 0x6000
	s_waitcnt lgkmcnt(1)
	v_mfma_f32_16x16x32_bf16 v[116:119], v[4:7], v[156:159], 0
	s_nop 0
	ds_read_b128 v[120:123], v168 offset:8192
	ds_read_b128 v[136:139], v168 offset:10240
	global_load_lds_dwordx4 v[164:165], off
	v_lshl_add_u64 v[164:165], v[154:155], 0, s[0:1]
	v_mfma_f32_16x16x32_bf16 v[112:115], v[0:3], v[156:159], 0
	v_lshl_add_u64 v[166:167], v[164:165], 0, s[38:39]
	s_mov_b32 m0, s15
	v_mfma_f32_16x16x32_bf16 v[108:111], v[12:15], v[156:159], 0
	global_load_lds_dwordx4 v[166:167], off
	v_lshl_add_u64 v[166:167], v[164:165], 0, s[82:83]
	v_mfma_f32_16x16x32_bf16 v[104:107], v[8:11], v[156:159], 0
	s_add_i32 m0, s14, 0xa000
	s_waitcnt lgkmcnt(2)
	v_mfma_f32_16x16x32_bf16 v[100:103], v[4:7], v[160:163], 0
	global_load_lds_dwordx4 v[166:167], off
	v_lshl_add_u64 v[166:167], v[164:165], 0, s[78:79]
	v_mfma_f32_16x16x32_bf16 v[96:99], v[0:3], v[160:163], 0
	s_add_i32 m0, s14, 0xc000
	v_lshl_add_u64 v[164:165], v[164:165], 0, s[2:3]
	v_mfma_f32_16x16x32_bf16 v[92:95], v[12:15], v[160:163], 0
	global_load_lds_dwordx4 v[166:167], off
	s_add_i32 m0, s14, 0xe000
	v_mfma_f32_16x16x32_bf16 v[88:91], v[8:11], v[160:163], 0
	global_load_lds_dwordx4 v[164:165], off
	s_waitcnt lgkmcnt(1)
	v_mfma_f32_16x16x32_bf16 v[84:87], v[4:7], v[120:123], 0
	ds_read_b128 v[156:159], v168 offset:12288
	ds_read_b128 v[160:163], v168 offset:14336
	ds_read_b128 v[172:175], v171 offset:33792
	ds_read_b128 v[176:179], v171 offset:35840
	ds_read_b128 v[180:183], v171 offset:37888
	ds_read_b128 v[184:187], v171 offset:39936
	v_mfma_f32_16x16x32_bf16 v[80:83], v[0:3], v[120:123], 0
	v_mfma_f32_16x16x32_bf16 v[76:79], v[12:15], v[120:123], 0
	v_mfma_f32_16x16x32_bf16 v[72:75], v[8:11], v[120:123], 0
	s_waitcnt lgkmcnt(6)
	v_mfma_f32_16x16x32_bf16 v[68:71], v[4:7], v[136:139], 0
	v_mfma_f32_16x16x32_bf16 v[64:67], v[0:3], v[136:139], 0
	v_mfma_f32_16x16x32_bf16 v[60:63], v[12:15], v[136:139], 0
	v_mfma_f32_16x16x32_bf16 v[56:59], v[8:11], v[136:139], 0
	s_waitcnt lgkmcnt(5)
	v_mfma_f32_16x16x32_bf16 v[52:55], v[4:7], v[156:159], 0
	ds_read_b128 v[120:123], v168 offset:1024
	ds_read_b128 v[164:167], v168 offset:3072
	v_mfma_f32_16x16x32_bf16 v[48:51], v[0:3], v[156:159], 0
	v_mfma_f32_16x16x32_bf16 v[44:47], v[12:15], v[156:159], 0
	v_mfma_f32_16x16x32_bf16 v[40:43], v[8:11], v[156:159], 0
	s_waitcnt lgkmcnt(6)
	v_mfma_f32_16x16x32_bf16 v[4:7], v[4:7], v[160:163], 0
	v_mfma_f32_16x16x32_bf16 v[0:3], v[0:3], v[160:163], 0
	v_mfma_f32_16x16x32_bf16 v[12:15], v[12:15], v[160:163], 0
	v_mfma_f32_16x16x32_bf16 v[8:11], v[8:11], v[160:163], 0
	s_waitcnt lgkmcnt(0)
	v_mfma_f32_16x16x32_bf16 v[148:151], v[172:175], v[120:123], v[148:151]
	ds_read_b128 v[32:35], v168 offset:5120
	ds_read_b128 v[36:39], v168 offset:7168
	v_mfma_f32_16x16x32_bf16 v[144:147], v[176:179], v[120:123], v[144:147]
	v_mfma_f32_16x16x32_bf16 v[140:143], v[180:183], v[120:123], v[140:143]
	v_mfma_f32_16x16x32_bf16 v[136:139], v[184:187], v[120:123], v[20:23]
	v_mfma_f32_16x16x32_bf16 v[132:135], v[172:175], v[164:167], v[132:135]
	v_mfma_f32_16x16x32_bf16 v[128:131], v[176:179], v[164:167], v[128:131]
	v_mfma_f32_16x16x32_bf16 v[124:127], v[180:183], v[164:167], v[124:127]
	v_mfma_f32_16x16x32_bf16 v[120:123], v[184:187], v[164:167], v[16:19]
	s_waitcnt lgkmcnt(1)
	v_mfma_f32_16x16x32_bf16 v[116:119], v[172:175], v[32:35], v[116:119]
	s_nop 0
	ds_read_b128 v[16:19], v168 offset:9216
	ds_read_b128 v[20:23], v168 offset:11264
	v_mfma_f32_16x16x32_bf16 v[112:115], v[176:179], v[32:35], v[112:115]
	v_mfma_f32_16x16x32_bf16 v[108:111], v[180:183], v[32:35], v[108:111]
	v_mfma_f32_16x16x32_bf16 v[104:107], v[184:187], v[32:35], v[104:107]
	s_waitcnt lgkmcnt(2)
	v_mfma_f32_16x16x32_bf16 v[100:103], v[172:175], v[36:39], v[100:103]
	v_mfma_f32_16x16x32_bf16 v[96:99], v[176:179], v[36:39], v[96:99]
	v_mfma_f32_16x16x32_bf16 v[92:95], v[180:183], v[36:39], v[92:95]
	v_mfma_f32_16x16x32_bf16 v[88:91], v[184:187], v[36:39], v[88:91]
	s_waitcnt lgkmcnt(1)
	v_mfma_f32_16x16x32_bf16 v[84:87], v[172:175], v[16:19], v[84:87]
	ds_read_b128 v[32:35], v168 offset:13312
	ds_read_b128 v[164:167], v168 offset:15360
	v_mfma_f32_16x16x32_bf16 v[80:83], v[176:179], v[16:19], v[80:83]
	v_mfma_f32_16x16x32_bf16 v[76:79], v[180:183], v[16:19], v[76:79]
	v_mfma_f32_16x16x32_bf16 v[72:75], v[184:187], v[16:19], v[72:75]
	s_waitcnt lgkmcnt(2)
	v_mfma_f32_16x16x32_bf16 v[68:71], v[172:175], v[20:23], v[68:71]
	v_mfma_f32_16x16x32_bf16 v[64:67], v[176:179], v[20:23], v[64:67]
	v_mfma_f32_16x16x32_bf16 v[60:63], v[180:183], v[20:23], v[60:63]
	v_mfma_f32_16x16x32_bf16 v[56:59], v[184:187], v[20:23], v[56:59]
	s_waitcnt lgkmcnt(1)
	v_mfma_f32_16x16x32_bf16 v[52:55], v[172:175], v[32:35], v[52:55]
	s_waitcnt vmcnt(0)
	s_waitcnt lgkmcnt(0)
	s_barrier
	ds_read_b128 v[20:23], v169
	ds_read_b128 v[16:19], v169 offset:2048
	ds_read_b128 v[188:191], v170 offset:32768
	ds_read_b128 v[192:195], v170 offset:34816
	ds_read_b128 v[196:199], v170 offset:36864
	ds_read_b128 v[200:203], v170 offset:38912
	v_mfma_f32_16x16x32_bf16 v[48:51], v[176:179], v[32:35], v[48:51]
	v_mfma_f32_16x16x32_bf16 v[44:47], v[180:183], v[32:35], v[44:47]
	v_mfma_f32_16x16x32_bf16 v[40:43], v[184:187], v[32:35], v[40:43]
	v_mfma_f32_16x16x32_bf16 v[36:39], v[172:175], v[164:167], v[4:7]
	v_mfma_f32_16x16x32_bf16 v[32:35], v[176:179], v[164:167], v[0:3]
	v_mfma_f32_16x16x32_bf16 v[28:31], v[180:183], v[164:167], v[12:15]
	v_mfma_f32_16x16x32_bf16 v[24:27], v[184:187], v[164:167], v[8:11]
	s_add_u32 s0, s0, 0x80
	s_addc_u32 s1, s1, 0
	s_add_i32 s22, s22, 0x10000
; #define WAIT_V(n) asm volatile("s_waitcnt vmcnt(%0)" ::"n"(n) : "memory")
;     ...
;     for (int t = 0; t < nt; ++t) {
;       const int cur = t & 1;
;       const char* sa = shm + cur * STAGE_B;
;       const char* sn = shm + (cur ^ 1) * STAGE_B;
;       const bool more = (t + 1 < nt) || (nitem < ntiles);
; #pragma unroll
;       for (int ks = 0; ks < 2; ++ks) {
; #pragma unroll
;         for (int p = 0; p < NP; ++p) {
;           const int q = ks * NP + p;
;           acc[p * 2][0] = __builtin_amdgcn_mfma_f32_16x16x32_bf16(Bq[BDBL ? ks : 0][0], Aq[q & 1][0], acc[p * 2][0], 0, 0, 0);
;           __builtin_amdgcn_sched_barrier(0);
;           if (q == 2 * NP - 1) {
;             WAIT_V(0);
;             __syncthreads();
;             if (more) {
;               if constexpr (BDBL) {
; #pragma unroll
;                 for (int n = 0; n < 4; ++n) Bq[0][n] = *(const bf16x8*)(sn + boff + (n * 2 + 0) * 1024);
;               }
; #pragma unroll
;               for (int i = 0; i < 2; ++i) Aq[0][i] = *(const bf16x8*)(sn + aoff + (i * 2 + 0) * 1024);
;             }
;           } else if (p + 1 < NP) {
; #pragma unroll
;             for (int i = 0; i < 2; ++i) Aq[(q + 1) & 1][i] = *(const bf16x8*)(sa + aoff + (((p + 1) * 2 + i) * 2 + ks) * 1024);
;           } else {
;             if constexpr (BDBL) {
; #pragma unroll
;               for (int n = 0; n < 4; ++n) Bq[1][n] = *(const bf16x8*)(sa + boff + (n * 2 + 1) * 1024);
;             }
; #pragma unroll
;             for (int i = 0; i < 2; ++i) Aq[(q + 1) & 1][i] = *(const bf16x8*)(sa + aoff + (i * 2 + 1) * 1024);
;           }
;           __builtin_amdgcn_sched_barrier(0);
; #pragma unroll
;           for (int i = 0; i < 2; ++i)
; #pragma unroll
;             for (int n = 0; n < 4; ++n)
;               if (i + n > 0)
;                 acc[p * 2 + i][n] = __builtin_amdgcn_mfma_f32_16x16x32_bf16(Bq[BDBL ? ks : 0][n], Aq[q & 1][i], acc[p * 2 + i][n], 0, 0, 0);
;           __builtin_amdgcn_sched_barrier(0);
;           if (q == GLDS_AT) {
;             if (t + 1 < nt) GLDS_STAGE(cur ^ 1, t + 1, Ab, Bb);
;             else if (nitem < ntiles) GLDS_STAGE(0, 0, nAb, nBb);
;             __builtin_amdgcn_sched_barrier(0);
;           }
.LBB0_742:
	s_waitcnt lgkmcnt(0)
	s_nop 0
	v_mfma_f32_16x16x32_bf16 v[148:151], v[188:191], v[20:23], v[148:151]
	s_and_b32 s14, s22, 0x10000
	s_xor_b32 s15, s14, 0x10000
	v_add_u32_e32 v168, s14, v222
	v_add_u32_e32 v169, s15, v222
	v_bitop3_b32 v170, s22, v223, v233 bitop3:0xce
	v_or_b32_e32 v171, s14, v223
	ds_read_b128 v[156:159], v168 offset:4096
	ds_read_b128 v[160:163], v168 offset:6144
	v_mfma_f32_16x16x32_bf16 v[144:147], v[192:195], v[20:23], v[144:147]
	s_add_i32 s14, s15, s4
	v_lshl_add_u64 v[164:165], v[152:153], 0, s[0:1]
	v_mfma_f32_16x16x32_bf16 v[140:143], v[196:199], v[20:23], v[140:143]
	v_lshl_add_u64 v[166:167], v[164:165], 0, s[38:39]
	s_mov_b32 m0, s14
	v_mfma_f32_16x16x32_bf16 v[20:23], v[200:203], v[20:23], v[136:139]
	s_add_i32 s15, s14, 0x8000
	global_load_lds_dwordx4 v[166:167], off
	v_mfma_f32_16x16x32_bf16 v[132:135], v[188:191], v[16:19], v[132:135]
	v_lshl_add_u64 v[166:167], v[164:165], 0, s[82:83]
	s_add_i32 m0, s14, 0x2000
	v_mfma_f32_16x16x32_bf16 v[128:131], v[192:195], v[16:19], v[128:131]
	global_load_lds_dwordx4 v[166:167], off
	v_lshl_add_u64 v[166:167], v[164:165], 0, s[78:79]
	v_mfma_f32_16x16x32_bf16 v[124:127], v[196:199], v[16:19], v[124:127]
	s_add_i32 m0, s14, 0x4000
	v_lshl_add_u64 v[164:165], v[164:165], 0, s[2:3]
	v_mfma_f32_16x16x32_bf16 v[16:19], v[200:203], v[16:19], v[120:123]
	global_load_lds_dwordx4 v[166:167], off
	s_add_i32 m0, s14, 0x6000
	s_waitcnt lgkmcnt(1)
	v_mfma_f32_16x16x32_bf16 v[116:119], v[188:191], v[156:159], v[116:119]
	s_nop 0
	ds_read_b128 v[120:123], v168 offset:8192
	ds_read_b128 v[136:139], v168 offset:10240
	global_load_lds_dwordx4 v[164:165], off
	v_lshl_add_u64 v[164:165], v[154:155], 0, s[0:1]
	v_mfma_f32_16x16x32_bf16 v[112:115], v[192:195], v[156:159], v[112:115]
	v_lshl_add_u64 v[166:167], v[164:165], 0, s[38:39]
	s_mov_b32 m0, s15
	v_mfma_f32_16x16x32_bf16 v[108:111], v[196:199], v[156:159], v[108:111]
	global_load_lds_dwordx4 v[166:167], off
	v_lshl_add_u64 v[166:167], v[164:165], 0, s[82:83]
	v_mfma_f32_16x16x32_bf16 v[104:107], v[200:203], v[156:159], v[104:107]
	s_add_i32 m0, s14, 0xa000
	s_waitcnt lgkmcnt(2)
	v_mfma_f32_16x16x32_bf16 v[100:103], v[188:191], v[160:163], v[100:103]
	global_load_lds_dwordx4 v[166:167], off
	v_lshl_add_u64 v[166:167], v[164:165], 0, s[78:79]
	v_mfma_f32_16x16x32_bf16 v[96:99], v[192:195], v[160:163], v[96:99]
	s_add_i32 m0, s14, 0xc000
	v_lshl_add_u64 v[164:165], v[164:165], 0, s[2:3]
	v_mfma_f32_16x16x32_bf16 v[92:95], v[196:199], v[160:163], v[92:95]
	global_load_lds_dwordx4 v[166:167], off
	s_add_i32 m0, s14, 0xe000
	v_mfma_f32_16x16x32_bf16 v[88:91], v[200:203], v[160:163], v[88:91]
	global_load_lds_dwordx4 v[164:165], off
	s_waitcnt lgkmcnt(1)
	v_mfma_f32_16x16x32_bf16 v[84:87], v[188:191], v[120:123], v[84:87]
	ds_read_b128 v[156:159], v168 offset:12288
	ds_read_b128 v[160:163], v168 offset:14336
	ds_read_b128 v[172:175], v171 offset:33792
	ds_read_b128 v[176:179], v171 offset:35840
	ds_read_b128 v[180:183], v171 offset:37888
	ds_read_b128 v[184:187], v171 offset:39936
	v_mfma_f32_16x16x32_bf16 v[80:83], v[192:195], v[120:123], v[80:83]
	v_mfma_f32_16x16x32_bf16 v[76:79], v[196:199], v[120:123], v[76:79]
	v_mfma_f32_16x16x32_bf16 v[72:75], v[200:203], v[120:123], v[72:75]
	s_waitcnt lgkmcnt(6)
	v_mfma_f32_16x16x32_bf16 v[68:71], v[188:191], v[136:139], v[68:71]
	v_mfma_f32_16x16x32_bf16 v[64:67], v[192:195], v[136:139], v[64:67]
	v_mfma_f32_16x16x32_bf16 v[60:63], v[196:199], v[136:139], v[60:63]
	v_mfma_f32_16x16x32_bf16 v[56:59], v[200:203], v[136:139], v[56:59]
	s_waitcnt lgkmcnt(5)
	v_mfma_f32_16x16x32_bf16 v[52:55], v[188:191], v[156:159], v[52:55]
	ds_read_b128 v[120:123], v168 offset:1024
	ds_read_b128 v[164:167], v168 offset:3072
	v_mfma_f32_16x16x32_bf16 v[48:51], v[192:195], v[156:159], v[48:51]
	v_mfma_f32_16x16x32_bf16 v[44:47], v[196:199], v[156:159], v[44:47]
	v_mfma_f32_16x16x32_bf16 v[40:43], v[200:203], v[156:159], v[40:43]
	s_waitcnt lgkmcnt(6)
	v_mfma_f32_16x16x32_bf16 v[4:7], v[188:191], v[160:163], v[36:39]
	v_mfma_f32_16x16x32_bf16 v[0:3], v[192:195], v[160:163], v[32:35]
	v_mfma_f32_16x16x32_bf16 v[12:15], v[196:199], v[160:163], v[28:31]
	v_mfma_f32_16x16x32_bf16 v[8:11], v[200:203], v[160:163], v[24:27]
	s_waitcnt lgkmcnt(0)
	v_mfma_f32_16x16x32_bf16 v[148:151], v[172:175], v[120:123], v[148:151]
	ds_read_b128 v[32:35], v168 offset:5120
	ds_read_b128 v[36:39], v168 offset:7168
	v_mfma_f32_16x16x32_bf16 v[144:147], v[176:179], v[120:123], v[144:147]
	v_mfma_f32_16x16x32_bf16 v[140:143], v[180:183], v[120:123], v[140:143]
	v_mfma_f32_16x16x32_bf16 v[136:139], v[184:187], v[120:123], v[20:23]
	v_mfma_f32_16x16x32_bf16 v[132:135], v[172:175], v[164:167], v[132:135]
	v_mfma_f32_16x16x32_bf16 v[128:131], v[176:179], v[164:167], v[128:131]
	v_mfma_f32_16x16x32_bf16 v[124:127], v[180:183], v[164:167], v[124:127]
	v_mfma_f32_16x16x32_bf16 v[120:123], v[184:187], v[164:167], v[16:19]
	s_waitcnt lgkmcnt(1)
	v_mfma_f32_16x16x32_bf16 v[116:119], v[172:175], v[32:35], v[116:119]
	s_nop 0
	ds_read_b128 v[16:19], v168 offset:9216
	ds_read_b128 v[20:23], v168 offset:11264
	v_mfma_f32_16x16x32_bf16 v[112:115], v[176:179], v[32:35], v[112:115]
	v_mfma_f32_16x16x32_bf16 v[108:111], v[180:183], v[32:35], v[108:111]
	v_mfma_f32_16x16x32_bf16 v[104:107], v[184:187], v[32:35], v[104:107]
	s_waitcnt lgkmcnt(2)
	v_mfma_f32_16x16x32_bf16 v[100:103], v[172:175], v[36:39], v[100:103]
	v_mfma_f32_16x16x32_bf16 v[96:99], v[176:179], v[36:39], v[96:99]
	v_mfma_f32_16x16x32_bf16 v[92:95], v[180:183], v[36:39], v[92:95]
	v_mfma_f32_16x16x32_bf16 v[88:91], v[184:187], v[36:39], v[88:91]
	s_waitcnt lgkmcnt(1)
	v_mfma_f32_16x16x32_bf16 v[84:87], v[172:175], v[16:19], v[84:87]
	ds_read_b128 v[32:35], v168 offset:13312
	ds_read_b128 v[164:167], v168 offset:15360
	v_mfma_f32_16x16x32_bf16 v[80:83], v[176:179], v[16:19], v[80:83]
	v_mfma_f32_16x16x32_bf16 v[76:79], v[180:183], v[16:19], v[76:79]
	v_mfma_f32_16x16x32_bf16 v[72:75], v[184:187], v[16:19], v[72:75]
	s_waitcnt lgkmcnt(2)
	v_mfma_f32_16x16x32_bf16 v[68:71], v[172:175], v[20:23], v[68:71]
	v_mfma_f32_16x16x32_bf16 v[64:67], v[176:179], v[20:23], v[64:67]
	v_mfma_f32_16x16x32_bf16 v[60:63], v[180:183], v[20:23], v[60:63]
	v_mfma_f32_16x16x32_bf16 v[56:59], v[184:187], v[20:23], v[56:59]
	s_waitcnt lgkmcnt(1)
	v_mfma_f32_16x16x32_bf16 v[52:55], v[172:175], v[32:35], v[52:55]
	s_waitcnt vmcnt(0)
	s_waitcnt lgkmcnt(0)
	s_barrier
; #define WAIT_V(n) asm volatile("s_waitcnt vmcnt(%0)" ::"n"(n) : "memory")
;     ...
;     for (int t = 0; t < nt; ++t) {
;       const int cur = t & 1;
;       const char* sa = shm + cur * STAGE_B;
;       const char* sn = shm + (cur ^ 1) * STAGE_B;
;       const bool more = (t + 1 < nt) || (nitem < ntiles);
; #pragma unroll
;       for (int ks = 0; ks < 2; ++ks) {
; #pragma unroll
;         for (int p = 0; p < NP; ++p) {
;           const int q = ks * NP + p;
;           acc[p * 2][0] = __builtin_amdgcn_mfma_f32_16x16x32_bf16(Bq[BDBL ? ks : 0][0], Aq[q & 1][0], acc[p * 2][0], 0, 0, 0);
;           __builtin_amdgcn_sched_barrier(0);
;           if (q == 2 * NP - 1) {
;             WAIT_V(0);
;             __syncthreads();
;             if (more) {
;               if constexpr (BDBL) {
; #pragma unroll
;                 for (int n = 0; n < 4; ++n) Bq[0][n] = *(const bf16x8*)(sn + boff + (n * 2 + 0) * 1024);
;               }
; #pragma unroll
;               for (int i = 0; i < 2; ++i) Aq[0][i] = *(const bf16x8*)(sn + aoff + (i * 2 + 0) * 1024);
;             }
;           } else if (p + 1 < NP) {
; #pragma unroll
;             for (int i = 0; i < 2; ++i) Aq[(q + 1) & 1][i] = *(const bf16x8*)(sa + aoff + (((p + 1) * 2 + i) * 2 + ks) * 1024);
;           } else {
;             if constexpr (BDBL) {
; #pragma unroll
;               for (int n = 0; n < 4; ++n) Bq[1][n] = *(const bf16x8*)(sa + boff + (n * 2 + 1) * 1024);
;             }
; #pragma unroll
;             for (int i = 0; i < 2; ++i) Aq[(q + 1) & 1][i] = *(const bf16x8*)(sa + aoff + (i * 2 + 1) * 1024);
;           }
;           __builtin_amdgcn_sched_barrier(0);
; #pragma unroll
;           for (int i = 0; i < 2; ++i)
; #pragma unroll
;             for (int n = 0; n < 4; ++n)
;               if (i + n > 0)
;                 acc[p * 2 + i][n] = __builtin_amdgcn_mfma_f32_16x16x32_bf16(Bq[BDBL ? ks : 0][n], Aq[q & 1][i], acc[p * 2 + i][n], 0, 0, 0);
;           __builtin_amdgcn_sched_barrier(0);
;           if (q == GLDS_AT) {
;             if (t + 1 < nt) GLDS_STAGE(cur ^ 1, t + 1, Ab, Bb);
;             else if (nitem < ntiles) GLDS_STAGE(0, 0, nAb, nBb);
;             __builtin_amdgcn_sched_barrier(0);
;           }
	ds_read_b128 v[20:23], v169
	ds_read_b128 v[16:19], v169 offset:2048
	ds_read_b128 v[188:191], v170 offset:32768
	ds_read_b128 v[192:195], v170 offset:34816
	ds_read_b128 v[196:199], v170 offset:36864
	ds_read_b128 v[200:203], v170 offset:38912
	v_mfma_f32_16x16x32_bf16 v[48:51], v[176:179], v[32:35], v[48:51]
	v_mfma_f32_16x16x32_bf16 v[44:47], v[180:183], v[32:35], v[44:47]
	v_mfma_f32_16x16x32_bf16 v[40:43], v[184:187], v[32:35], v[40:43]
	v_mfma_f32_16x16x32_bf16 v[36:39], v[172:175], v[164:167], v[4:7]
	v_mfma_f32_16x16x32_bf16 v[32:35], v[176:179], v[164:167], v[0:3]
	v_mfma_f32_16x16x32_bf16 v[28:31], v[180:183], v[164:167], v[12:15]
	v_mfma_f32_16x16x32_bf16 v[24:27], v[184:187], v[164:167], v[8:11]
	s_add_u32 s0, s0, 0x80
	s_addc_u32 s1, s1, 0
	s_add_i32 s22, s22, 0x10000
	s_cmpk_eq_i32 s0, 0x780
	s_cbranch_scc0 .LBB0_742
	s_waitcnt lgkmcnt(0)
	v_mov_b64_e32 v[4:5], v[188:189]
	v_mov_b64_e32 v[6:7], v[190:191]
	v_mov_b64_e32 v[0:1], v[192:193]
	v_mov_b64_e32 v[2:3], v[194:195]
	v_mov_b64_e32 v[12:13], v[196:197]
	v_mov_b64_e32 v[14:15], v[198:199]
	v_mov_b64_e32 v[8:9], v[200:201]
	v_mov_b64_e32 v[10:11], v[202:203]
	s_nop 1
	s_waitcnt lgkmcnt(3)
	v_mfma_f32_16x16x32_bf16 v[148:151], v[4:7], v[20:23], v[148:151]
	v_add_u32_e32 v224, 0x10000, v222
	ds_read_b128 v[152:155], v224 offset:4096
	ds_read_b128 v[156:159], v224 offset:6144
	s_waitcnt lgkmcnt(4)
	v_mfma_f32_16x16x32_bf16 v[164:167], v[0:3], v[20:23], v[144:147]
	s_waitcnt lgkmcnt(3)
	v_mfma_f32_16x16x32_bf16 v[140:143], v[12:15], v[20:23], v[140:143]
	s_waitcnt lgkmcnt(2)
	v_mfma_f32_16x16x32_bf16 v[20:23], v[8:11], v[20:23], v[136:139]
	v_mfma_f32_16x16x32_bf16 v[132:135], v[4:7], v[16:19], v[132:135]
	v_mfma_f32_16x16x32_bf16 v[168:171], v[0:3], v[16:19], v[128:131]
	v_mfma_f32_16x16x32_bf16 v[124:127], v[12:15], v[16:19], v[124:127]
	v_mfma_f32_16x16x32_bf16 v[16:19], v[8:11], v[16:19], v[120:123]
	s_waitcnt lgkmcnt(1)
	v_mfma_f32_16x16x32_bf16 v[116:119], v[4:7], v[152:155], v[116:119]
	s_nop 0
	ds_read_b128 v[120:123], v224 offset:8192
	ds_read_b128 v[128:131], v224 offset:10240
	v_mfma_f32_16x16x32_bf16 v[172:175], v[0:3], v[152:155], v[112:115]
	v_mfma_f32_16x16x32_bf16 v[108:111], v[12:15], v[152:155], v[108:111]
	v_mfma_f32_16x16x32_bf16 v[176:179], v[8:11], v[152:155], v[104:107]
	s_waitcnt lgkmcnt(2)
	v_mfma_f32_16x16x32_bf16 v[100:103], v[4:7], v[156:159], v[100:103]
	v_mfma_f32_16x16x32_bf16 v[180:183], v[0:3], v[156:159], v[96:99]
	v_mfma_f32_16x16x32_bf16 v[92:95], v[12:15], v[156:159], v[92:95]
	v_mfma_f32_16x16x32_bf16 v[184:187], v[8:11], v[156:159], v[88:91]
	s_waitcnt lgkmcnt(1)
	v_mfma_f32_16x16x32_bf16 v[84:87], v[4:7], v[120:123], v[84:87]
	s_nop 0
	ds_read_b128 v[88:91], v224 offset:12288
	ds_read_b128 v[96:99], v224 offset:14336
	v_mfma_f32_16x16x32_bf16 v[188:191], v[0:3], v[120:123], v[80:83]
	v_mfma_f32_16x16x32_bf16 v[76:79], v[12:15], v[120:123], v[76:79]
	v_mfma_f32_16x16x32_bf16 v[192:195], v[8:11], v[120:123], v[72:75]
	s_waitcnt lgkmcnt(2)
	v_mfma_f32_16x16x32_bf16 v[68:71], v[4:7], v[128:131], v[68:71]
	v_mfma_f32_16x16x32_bf16 v[196:199], v[0:3], v[128:131], v[64:67]
	v_mfma_f32_16x16x32_bf16 v[60:63], v[12:15], v[128:131], v[60:63]
	v_mfma_f32_16x16x32_bf16 v[200:203], v[8:11], v[128:131], v[56:59]
	s_waitcnt lgkmcnt(1)
	v_mfma_f32_16x16x32_bf16 v[204:207], v[4:7], v[88:91], v[52:55]
	ds_read_b128 v[64:67], v224 offset:1024
	ds_read_b128 v[56:59], v224 offset:3072
	v_mfma_f32_16x16x32_bf16 v[52:55], v[0:3], v[88:91], v[48:51]
	v_mfma_f32_16x16x32_bf16 v[44:47], v[12:15], v[88:91], v[44:47]
	v_mfma_f32_16x16x32_bf16 v[152:155], v[8:11], v[88:91], v[40:43]
	s_waitcnt lgkmcnt(2)
	v_mfma_f32_16x16x32_bf16 v[36:39], v[4:7], v[96:99], v[36:39]
	v_mfma_f32_16x16x32_bf16 v[156:159], v[0:3], v[96:99], v[32:35]
	v_mfma_f32_16x16x32_bf16 v[28:31], v[12:15], v[96:99], v[28:31]
	v_mfma_f32_16x16x32_bf16 v[160:163], v[8:11], v[96:99], v[24:27]
	v_cndmask_b32_e64 v0, 0, 1, s[6:7]
	v_cmp_ne_u32_e64 s[0:1], 1, v0
	s_andn2_b64 vcc, exec, s[6:7]
	s_cbranch_vccnz .LBB0_745
	s_mov_b32 m0, s4
	v_lshl_add_u64 v[0:1], s[8:9], 0, v[208:209]
	v_lshl_add_u64 v[4:5], v[0:1], 0, s[76:77]
	global_load_lds_dwordx4 v[0:1], off
	s_add_i32 m0, s4, 0x2000
	v_lshl_add_u64 v[6:7], v[0:1], 0, s[96:97]
	global_load_lds_dwordx4 v[4:5], off
	s_add_i32 m0, s4, 0x4000
	v_lshl_add_u64 v[8:9], v[0:1], 0, s[70:71]
	global_load_lds_dwordx4 v[6:7], off
	s_add_i32 m0, s4, 0x6000
	v_lshl_add_u64 v[2:3], s[10:11], 0, v[208:209]
	global_load_lds_dwordx4 v[8:9], off
	s_add_i32 m0, s4, 0x8000
	v_lshl_add_u64 v[10:11], v[2:3], 0, s[76:77]
	global_load_lds_dwordx4 v[2:3], off
	s_add_i32 m0, s4, 0xa000
	v_lshl_add_u64 v[12:13], v[2:3], 0, s[96:97]
	global_load_lds_dwordx4 v[10:11], off
	s_add_i32 m0, s4, 0xc000
	v_lshl_add_u64 v[14:15], v[2:3], 0, s[70:71]
	global_load_lds_dwordx4 v[12:13], off
	s_add_i32 m0, s4, 0xe000
	s_nop 0
	global_load_lds_dwordx4 v[14:15], off
